# GEMM unit transitions (MLP-up, conv-in): drop vmcnt(0) drain before next rstd loads, wait only for the rstd loads after the epilogue stores
# speedup vs baseline: 1.0085x; 1.0085x over previous
; __device__ __forceinline__ int opaque_tid() { int t = threadIdx.x; asm volatile("" : "+v"(t)); return t; }
; __device__ __forceinline__ u32x4 pack8(f32x4 a, f32x4 b) { u32x4 w; w.x = cvt_pk_bf16(a[0], a[1]); w.y = cvt_pk_bf16(a[2], a[3]); w.z = cvt_pk_bf16(b[0], b[1]); w.w = cvt_pk_bf16(b[2], b[3]); return w; }
; __device__ __forceinline__ bf16x8 pack8(f32x4 a, f32x4 b) { u32x4 w = {cvtpk(a[0], a[1]), cvtpk(a[2], a[3]), cvtpk(b[0], b[1]), cvtpk(b[2], b[3])}; return *reinterpret_cast<bf16x8*>(&w); }
; __device__ __forceinline__ void rstd_load(const float* ss, RstdIni& ini, int pm) {
;     const int tid = opaque_tid();
;     const f32x4* q = (const f32x4*)(ss + (size_t)(pm * BM + (tid >> 1)) * 16 + (tid & 1) * 8);
;     ini.a = q[0]; ini.b = q[1];
; }
;     PG8_RSTD_HOOKS
;     __device__ __forceinline__ void operator()(const f32x4 (&acc)[2][2][4][2], const Unit& u, int wr, int wc, int fr, int fq, int par) const {
;         const int row0 = u.pm * BM + wr * 64 + fr, col0 = u.pn * BM + wc * 32 + 8 * fq;
;         float rsv[2][4]; rstd_read(tab, par, wr, fr, rsv);
; #pragma unroll
;         for (int ai = 0; ai < 2; ++ai)
; #pragma unroll
;             for (int m = 0; m < 4; ++m) { const float rs = rsv[ai][m];
;                 bf16_t* rowp = H + ((size_t)(u.pm * 64 + u.pn * 4 + wc) * 256 + (ai * HALF + wr * 64 + m * 16 + fr)) * 64 + 8 * fq;
; #pragma unroll
;                 for (int bj = 0; bj < 2; ++bj) { f32x4 v0 = acc[ai][bj][m][0] * rs, v1 = acc[ai][bj][m][1] * rs;
; #pragma unroll
;                     for (int j = 0; j < 4; ++j) { const float a = fmaxf(v0[j], 0.f), b = fmaxf(v1[j], 0.f); v0[j] = a * a; v1[j] = b * b; }
;                     *(u32x4*)(rowp + bj * 32) = pack8(v0, v1); } }
;     }
.LBB0_49:
	v_cndmask_b32_e64 v168, 0, 1, s[36:37]
	v_readlane_b32 s88, v255, 45
	v_cmp_ne_u32_e64 s[38:39], 1, v168
	s_andn2_b64 vcc, exec, s[36:37]
	v_readlane_b32 s89, v255, 46
	s_cbranch_vccnz .LBB0_51
	v_mov_b32_e32 v4, v0
	v_readlane_b32 s0, v253, 39
	v_ashrrev_i32_e32 v2, 1, v4
	v_lshl_add_u32 v2, s18, 8, v2
	v_ashrrev_i32_e32 v3, 31, v2
	v_lshlrev_b64 v[2:3], 6, v[2:3]
	v_readlane_b32 s1, v253, 40
	v_lshlrev_b32_e32 v4, 5, v4
	v_and_b32_e32 v4, 32, v4
	v_lshl_add_u64 v[2:3], s[0:1], 0, v[2:3]
	v_mov_b32_e32 v5, v99
	v_lshl_add_u64 v[6:7], v[2:3], 0, v[4:5]
	global_load_dwordx4 v[2:5], v[6:7], off offset:16
	s_nop 0
	global_load_dwordx4 v[6:9], v[6:7], off
.LBB0_51:
	s_lshl_b32 s0, s80, 10
	s_and_b32 s0, s0, 0x400
	v_add_u32_e32 v168, s0, v178
	s_lshl_b32 s0, s47, 6
	s_lshl_b32 s1, s46, 2
	s_add_i32 s0, s0, s1
	ds_read2_b32 v[172:173], v168 offset1:16
	ds_read2_b32 v[174:175], v168 offset0:32 offset1:48
	ds_read2_b32 v[170:171], v168 offset0:128 offset1:144
	ds_read2_b32 v[168:169], v168 offset0:160 offset1:176
	s_or_b32 s0, s0, s43
	s_ashr_i32 s1, s0, 31
	s_lshl_b64 s[0:1], s[0:1], 15
	s_waitcnt lgkmcnt(0)
	v_pk_mul_f32 v[132:133], v[132:133], v[172:173] op_sel_hi:[1,0]
	s_add_u32 s22, s88, s0
	v_pk_mul_f32 v[136:137], v[136:137], v[172:173] op_sel_hi:[1,0]
	v_pk_mul_f32 v[134:135], v[134:135], v[172:173] op_sel_hi:[1,0]
	v_max_f32_e32 v132, 0, v132
	s_addc_u32 s23, s89, s1
	v_pk_mul_f32 v[138:139], v[138:139], v[172:173] op_sel_hi:[1,0]
	v_mul_f32_e32 v182, v132, v132
	v_max_f32_e32 v132, 0, v137
	v_max_f32_e32 v133, 0, v133
	v_max_f32_e32 v134, 0, v134
	v_lshl_add_u64 v[180:181], s[22:23], 0, v[148:149]
	v_max_f32_e32 v136, 0, v136
	v_mul_f32_e32 v132, v132, v132
	v_mul_f32_e32 v137, v133, v133
	v_max_f32_e32 v133, 0, v138
	v_mul_f32_e32 v138, v134, v134
	v_max_f32_e32 v134, 0, v139
	v_max_f32_e32 v135, 0, v135
	v_pk_mul_f32 v[126:127], v[126:127], v[172:173] op_sel_hi:[1,0]
	v_pk_mul_f32 v[124:125], v[124:125], v[172:173] op_sel_hi:[1,0]
	v_lshl_add_u64 v[180:181], v[180:181], 0, v[98:99]
	v_mul_f32_e32 v136, v136, v136
	v_mul_f32_e32 v133, v133, v133
	v_mul_f32_e32 v134, v134, v134
	v_mul_f32_e32 v135, v135, v135
	v_cvt_pk_bf16_f32 v132, v136, v132
	v_pk_mul_f32 v[130:131], v[130:131], v[172:173] op_sel_hi:[1,0]
	v_pk_mul_f32 v[128:129], v[128:129], v[172:173] op_sel_hi:[1,0]
	v_max_f32_e32 v124, 0, v124
	v_max_f32_e32 v125, 0, v125
	v_max_f32_e32 v126, 0, v126
	v_cvt_pk_bf16_f32 v133, v133, v134
	v_cvt_pk_bf16_f32 v134, v182, v137
	v_cvt_pk_bf16_f32 v135, v138, v135
	global_store_dwordx4 v[180:181], v[132:135], off sc1
	v_max_f32_e32 v128, 0, v128
	v_max_f32_e32 v127, 0, v127
	v_mul_f32_e32 v132, v124, v124
	v_max_f32_e32 v124, 0, v129
	v_mul_f32_e32 v129, v125, v125
	v_max_f32_e32 v125, 0, v130
	v_mul_f32_e32 v130, v126, v126
	v_max_f32_e32 v126, 0, v131
	v_mul_f32_e32 v124, v124, v124
	v_mul_f32_e32 v125, v125, v125
	v_mul_f32_e32 v126, v126, v126
	v_mul_f32_e32 v128, v128, v128
	v_mul_f32_e32 v127, v127, v127
	v_cvt_pk_bf16_f32 v124, v128, v124
	v_cvt_pk_bf16_f32 v125, v125, v126
	v_cvt_pk_bf16_f32 v126, v132, v129
	v_cvt_pk_bf16_f32 v127, v130, v127
	global_store_dwordx4 v[180:181], v[124:127], off offset:64 sc1
	v_pk_mul_f32 v[100:101], v[100:101], v[174:175] op_sel_hi:[1,0]
	v_pk_mul_f32 v[104:105], v[104:105], v[174:175] op_sel_hi:[1,0]
	v_mov_b32_e32 v126, v173
	v_pk_mul_f32 v[116:117], v[116:117], v[126:127] op_sel_hi:[1,0]
	v_pk_mul_f32 v[120:121], v[120:121], v[126:127] op_sel_hi:[1,0]
	v_pk_mul_f32 v[118:119], v[118:119], v[126:127] op_sel_hi:[1,0]
	v_max_f32_e32 v116, 0, v116
	v_pk_mul_f32 v[122:123], v[122:123], v[126:127] op_sel_hi:[1,0]
	v_mul_f32_e32 v127, v116, v116
	v_max_f32_e32 v116, 0, v121
	v_max_f32_e32 v117, 0, v117
	v_max_f32_e32 v118, 0, v118
	v_lshl_add_u64 v[124:125], s[22:23], 0, v[150:151]
	v_max_f32_e32 v120, 0, v120
	v_mul_f32_e32 v116, v116, v116
	v_mul_f32_e32 v121, v117, v117
	v_max_f32_e32 v117, 0, v122
	v_mul_f32_e32 v122, v118, v118
	v_max_f32_e32 v118, 0, v123
	v_max_f32_e32 v119, 0, v119
	v_pk_mul_f32 v[110:111], v[110:111], v[126:127] op_sel_hi:[1,0]
	v_pk_mul_f32 v[108:109], v[108:109], v[126:127] op_sel_hi:[1,0]
	v_lshl_add_u64 v[124:125], v[124:125], 0, v[98:99]
	v_mul_f32_e32 v120, v120, v120
	v_mul_f32_e32 v117, v117, v117
	v_mul_f32_e32 v118, v118, v118
	v_mul_f32_e32 v119, v119, v119
	v_cvt_pk_bf16_f32 v116, v120, v116
	v_pk_mul_f32 v[114:115], v[114:115], v[126:127] op_sel_hi:[1,0]
	v_pk_mul_f32 v[112:113], v[112:113], v[126:127] op_sel_hi:[1,0]
	v_max_f32_e32 v108, 0, v108
	v_max_f32_e32 v109, 0, v109
	v_max_f32_e32 v110, 0, v110
	v_cvt_pk_bf16_f32 v117, v117, v118
	v_cvt_pk_bf16_f32 v118, v127, v121
	v_cvt_pk_bf16_f32 v119, v122, v119
	global_store_dwordx4 v[124:125], v[116:119], off sc1
	v_max_f32_e32 v112, 0, v112
	v_max_f32_e32 v111, 0, v111
	v_mul_f32_e32 v116, v108, v108
	v_max_f32_e32 v108, 0, v113
	v_mul_f32_e32 v113, v109, v109
	v_max_f32_e32 v109, 0, v114
	v_mul_f32_e32 v114, v110, v110
	v_max_f32_e32 v110, 0, v115
	v_mul_f32_e32 v108, v108, v108
	v_mul_f32_e32 v109, v109, v109
	v_mul_f32_e32 v110, v110, v110
	v_mul_f32_e32 v112, v112, v112
	v_mul_f32_e32 v111, v111, v111
	v_cvt_pk_bf16_f32 v108, v112, v108
	v_cvt_pk_bf16_f32 v109, v109, v110
	v_cvt_pk_bf16_f32 v110, v116, v113
	v_pk_mul_f32 v[102:103], v[102:103], v[174:175] op_sel_hi:[1,0]
	v_max_f32_e32 v100, 0, v100
	v_cvt_pk_bf16_f32 v111, v114, v111
	global_store_dwordx4 v[124:125], v[108:111], off offset:64 sc1
	v_pk_mul_f32 v[106:107], v[106:107], v[174:175] op_sel_hi:[1,0]
	v_max_f32_e32 v101, 0, v101
	v_mul_f32_e32 v110, v100, v100
	v_max_f32_e32 v100, 0, v105
	v_max_f32_e32 v102, 0, v102
; __device__ __forceinline__ u32x4 pack8(f32x4 a, f32x4 b) { u32x4 w; w.x = cvt_pk_bf16(a[0], a[1]); w.y = cvt_pk_bf16(a[2], a[3]); w.z = cvt_pk_bf16(b[0], b[1]); w.w = cvt_pk_bf16(b[2], b[3]); return w; }
; __device__ __forceinline__ bf16x8 pack8(f32x4 a, f32x4 b) { u32x4 w = {cvtpk(a[0], a[1]), cvtpk(a[2], a[3]), cvtpk(b[0], b[1]), cvtpk(b[2], b[3])}; return *reinterpret_cast<bf16x8*>(&w); }
;     PG8_RSTD_HOOKS
;     __device__ __forceinline__ void operator()(const f32x4 (&acc)[2][2][4][2], const Unit& u, int wr, int wc, int fr, int fq, int par) const {
;     ...
;             for (int m = 0; m < 4; ++m) { const float rs = rsv[ai][m];
;                 bf16_t* rowp = H + ((size_t)(u.pm * 64 + u.pn * 4 + wc) * 256 + (ai * HALF + wr * 64 + m * 16 + fr)) * 64 + 8 * fq;
; #pragma unroll
;                 for (int bj = 0; bj < 2; ++bj) { f32x4 v0 = acc[ai][bj][m][0] * rs, v1 = acc[ai][bj][m][1] * rs;
; #pragma unroll
;                     for (int j = 0; j < 4; ++j) { const float a = fmaxf(v0[j], 0.f), b = fmaxf(v1[j], 0.f); v0[j] = a * a; v1[j] = b * b; }
;                     *(u32x4*)(rowp + bj * 32) = pack8(v0, v1); } }
	v_lshl_add_u64 v[108:109], s[22:23], 0, v[152:153]
	v_max_f32_e32 v104, 0, v104
	v_mul_f32_e32 v100, v100, v100
	v_mul_f32_e32 v105, v101, v101
	v_max_f32_e32 v101, 0, v106
	v_mul_f32_e32 v106, v102, v102
	v_max_f32_e32 v102, 0, v107
	v_max_f32_e32 v103, 0, v103
	v_pk_mul_f32 v[92:93], v[92:93], v[174:175] op_sel_hi:[1,0]
	v_pk_mul_f32 v[90:91], v[90:91], v[174:175] op_sel_hi:[1,0]
	v_lshl_add_u64 v[108:109], v[108:109], 0, v[98:99]
	v_mul_f32_e32 v104, v104, v104
	v_mul_f32_e32 v101, v101, v101
	v_mul_f32_e32 v102, v102, v102
	v_mul_f32_e32 v103, v103, v103
	v_cvt_pk_bf16_f32 v100, v104, v100
	v_pk_mul_f32 v[96:97], v[96:97], v[174:175] op_sel_hi:[1,0]
	v_pk_mul_f32 v[94:95], v[94:95], v[174:175] op_sel_hi:[1,0]
	v_max_f32_e32 v90, 0, v90
	v_max_f32_e32 v91, 0, v91
	v_max_f32_e32 v92, 0, v92
	v_cvt_pk_bf16_f32 v101, v101, v102
	v_cvt_pk_bf16_f32 v102, v110, v105
	v_cvt_pk_bf16_f32 v103, v106, v103
	global_store_dwordx4 v[108:109], v[100:103], off sc1
	v_max_f32_e32 v94, 0, v94
	v_max_f32_e32 v93, 0, v93
	v_mul_f32_e32 v100, v90, v90
	v_max_f32_e32 v90, 0, v95
	v_mul_f32_e32 v95, v91, v91
	v_max_f32_e32 v91, 0, v96
	v_mul_f32_e32 v96, v92, v92
	v_max_f32_e32 v92, 0, v97
	v_mul_f32_e32 v90, v90, v90
	v_mul_f32_e32 v91, v91, v91
	v_mul_f32_e32 v92, v92, v92
	v_mul_f32_e32 v94, v94, v94
	v_mul_f32_e32 v93, v93, v93
	v_cvt_pk_bf16_f32 v90, v94, v90
	v_cvt_pk_bf16_f32 v91, v91, v92
	v_cvt_pk_bf16_f32 v92, v100, v95
	v_cvt_pk_bf16_f32 v93, v96, v93
	global_store_dwordx4 v[108:109], v[90:93], off offset:64 sc1
	v_pk_mul_f32 v[66:67], v[66:67], v[170:171] op_sel_hi:[1,0]
	v_pk_mul_f32 v[70:71], v[70:71], v[170:171] op_sel_hi:[1,0]
	v_mov_b32_e32 v92, v175
	v_pk_mul_f32 v[82:83], v[82:83], v[92:93] op_sel_hi:[1,0]
	v_pk_mul_f32 v[86:87], v[86:87], v[92:93] op_sel_hi:[1,0]
	v_pk_mul_f32 v[84:85], v[84:85], v[92:93] op_sel_hi:[1,0]
	v_max_f32_e32 v82, 0, v82
	v_pk_mul_f32 v[88:89], v[88:89], v[92:93] op_sel_hi:[1,0]
	v_mul_f32_e32 v93, v82, v82
	v_max_f32_e32 v82, 0, v87
	v_max_f32_e32 v83, 0, v83
	v_max_f32_e32 v84, 0, v84
	v_lshl_add_u64 v[90:91], s[22:23], 0, v[154:155]
	v_max_f32_e32 v86, 0, v86
	v_mul_f32_e32 v82, v82, v82
	v_mul_f32_e32 v87, v83, v83
	v_max_f32_e32 v83, 0, v88
	v_mul_f32_e32 v88, v84, v84
	v_max_f32_e32 v84, 0, v89
	v_max_f32_e32 v85, 0, v85
	v_pk_mul_f32 v[76:77], v[76:77], v[92:93] op_sel_hi:[1,0]
	v_pk_mul_f32 v[74:75], v[74:75], v[92:93] op_sel_hi:[1,0]
	v_lshl_add_u64 v[90:91], v[90:91], 0, v[98:99]
	v_mul_f32_e32 v86, v86, v86
	v_mul_f32_e32 v83, v83, v83
	v_mul_f32_e32 v84, v84, v84
	v_mul_f32_e32 v85, v85, v85
	v_cvt_pk_bf16_f32 v82, v86, v82
	v_pk_mul_f32 v[80:81], v[80:81], v[92:93] op_sel_hi:[1,0]
	v_pk_mul_f32 v[78:79], v[78:79], v[92:93] op_sel_hi:[1,0]
	v_max_f32_e32 v74, 0, v74
	v_max_f32_e32 v75, 0, v75
	v_max_f32_e32 v76, 0, v76
	v_cvt_pk_bf16_f32 v83, v83, v84
	v_cvt_pk_bf16_f32 v84, v93, v87
	v_cvt_pk_bf16_f32 v85, v88, v85
	global_store_dwordx4 v[90:91], v[82:85], off sc1
	v_max_f32_e32 v78, 0, v78
	v_max_f32_e32 v77, 0, v77
	v_mul_f32_e32 v82, v74, v74
	v_max_f32_e32 v74, 0, v79
	v_mul_f32_e32 v79, v75, v75
	v_max_f32_e32 v75, 0, v80
	v_mul_f32_e32 v80, v76, v76
	v_max_f32_e32 v76, 0, v81
	v_mul_f32_e32 v74, v74, v74
	v_mul_f32_e32 v75, v75, v75
	v_mul_f32_e32 v76, v76, v76
	v_mul_f32_e32 v78, v78, v78
	v_mul_f32_e32 v77, v77, v77
	v_cvt_pk_bf16_f32 v74, v78, v74
	v_cvt_pk_bf16_f32 v75, v75, v76
	v_cvt_pk_bf16_f32 v76, v82, v79
	v_pk_mul_f32 v[68:69], v[68:69], v[170:171] op_sel_hi:[1,0]
	v_max_f32_e32 v66, 0, v66
	v_cvt_pk_bf16_f32 v77, v80, v77
	global_store_dwordx4 v[90:91], v[74:77], off offset:64 sc1
	v_pk_mul_f32 v[72:73], v[72:73], v[170:171] op_sel_hi:[1,0]
	v_max_f32_e32 v67, 0, v67
	v_mul_f32_e32 v76, v66, v66
	v_max_f32_e32 v66, 0, v71
	v_max_f32_e32 v68, 0, v68
	v_lshl_add_u64 v[74:75], s[22:23], 0, v[156:157]
	v_max_f32_e32 v70, 0, v70
	v_mul_f32_e32 v66, v66, v66
	v_mul_f32_e32 v71, v67, v67
	v_max_f32_e32 v67, 0, v72
	v_mul_f32_e32 v72, v68, v68
	v_max_f32_e32 v68, 0, v73
	v_max_f32_e32 v69, 0, v69
	v_pk_mul_f32 v[60:61], v[60:61], v[170:171] op_sel_hi:[1,0]
	v_pk_mul_f32 v[58:59], v[58:59], v[170:171] op_sel_hi:[1,0]
	v_lshl_add_u64 v[74:75], v[74:75], 0, v[98:99]
	v_mul_f32_e32 v70, v70, v70
	v_mul_f32_e32 v67, v67, v67
	v_mul_f32_e32 v68, v68, v68
	v_mul_f32_e32 v69, v69, v69
	v_cvt_pk_bf16_f32 v66, v70, v66
	v_pk_mul_f32 v[64:65], v[64:65], v[170:171] op_sel_hi:[1,0]
	v_pk_mul_f32 v[62:63], v[62:63], v[170:171] op_sel_hi:[1,0]
	v_max_f32_e32 v58, 0, v58
	v_max_f32_e32 v59, 0, v59
	v_max_f32_e32 v60, 0, v60
	v_cvt_pk_bf16_f32 v67, v67, v68
	v_cvt_pk_bf16_f32 v68, v76, v71
	v_cvt_pk_bf16_f32 v69, v72, v69
	global_store_dwordx4 v[74:75], v[66:69], off sc1
	v_max_f32_e32 v62, 0, v62
	v_max_f32_e32 v61, 0, v61
	v_mul_f32_e32 v66, v58, v58
	v_max_f32_e32 v58, 0, v63
	v_mul_f32_e32 v63, v59, v59
	v_max_f32_e32 v59, 0, v64
	v_mul_f32_e32 v64, v60, v60
	v_max_f32_e32 v60, 0, v65
	v_mul_f32_e32 v58, v58, v58
	v_mul_f32_e32 v59, v59, v59
	v_mul_f32_e32 v60, v60, v60
	v_mul_f32_e32 v62, v62, v62
	v_mul_f32_e32 v61, v61, v61
	v_cvt_pk_bf16_f32 v58, v62, v58
	v_cvt_pk_bf16_f32 v59, v59, v60
	v_cvt_pk_bf16_f32 v60, v66, v63
	v_cvt_pk_bf16_f32 v61, v64, v61
	global_store_dwordx4 v[74:75], v[58:61], off offset:64 sc1
	v_pk_mul_f32 v[34:35], v[34:35], v[168:169] op_sel_hi:[1,0]
	v_pk_mul_f32 v[38:39], v[38:39], v[168:169] op_sel_hi:[1,0]
	v_mov_b32_e32 v60, v171
	v_pk_mul_f32 v[50:51], v[50:51], v[60:61] op_sel_hi:[1,0]
	v_pk_mul_f32 v[54:55], v[54:55], v[60:61] op_sel_hi:[1,0]
	v_pk_mul_f32 v[52:53], v[52:53], v[60:61] op_sel_hi:[1,0]
	v_max_f32_e32 v50, 0, v50
	v_pk_mul_f32 v[56:57], v[56:57], v[60:61] op_sel_hi:[1,0]
; __device__ __forceinline__ int opaque_tid() { int t = threadIdx.x; asm volatile("" : "+v"(t)); return t; }
; #define PG8_LAS __attribute__((address_space(3)))
; __device__ __forceinline__ u32x4 pack8(f32x4 a, f32x4 b) { u32x4 w; w.x = cvt_pk_bf16(a[0], a[1]); w.y = cvt_pk_bf16(a[2], a[3]); w.z = cvt_pk_bf16(b[0], b[1]); w.w = cvt_pk_bf16(b[2], b[3]); return w; }
; __device__ __forceinline__ bf16x8 pack8(f32x4 a, f32x4 b) { u32x4 w = {cvtpk(a[0], a[1]), cvtpk(a[2], a[3]), cvtpk(b[0], b[1]), cvtpk(b[2], b[3])}; return *reinterpret_cast<bf16x8*>(&w); }
; __device__ __forceinline__ void rstd_store(PG8_LAS float* tab, const RstdIni& ini, int par) {
;     const int tid = opaque_tid();
;     float s = ((ini.a[0] + ini.a[1]) + (ini.a[2] + ini.a[3])) + ((ini.b[0] + ini.b[1]) + (ini.b[2] + ini.b[3]));
;     s += __shfl_xor(s, 1);
;     if (!(tid & 1)) tab[par * BM + (tid >> 1)] = __builtin_amdgcn_rsqf(s * (1.0f / 1024.0f) + 1e-6f);
; }
;     PG8_RSTD_HOOKS
;     __device__ __forceinline__ void operator()(const f32x4 (&acc)[2][2][4][2], const Unit& u, int wr, int wc, int fr, int fq, int par) const {
;     ...
;                 for (int bj = 0; bj < 2; ++bj) { f32x4 v0 = acc[ai][bj][m][0] * rs, v1 = acc[ai][bj][m][1] * rs;
; #pragma unroll
;                     for (int j = 0; j < 4; ++j) { const float a = fmaxf(v0[j], 0.f), b = fmaxf(v1[j], 0.f); v0[j] = a * a; v1[j] = b * b; }
;                     *(u32x4*)(rowp + bj * 32) = pack8(v0, v1); } }
	v_mul_f32_e32 v61, v50, v50
	v_max_f32_e32 v50, 0, v55
	v_max_f32_e32 v51, 0, v51
	v_max_f32_e32 v52, 0, v52
	v_lshl_add_u64 v[58:59], s[22:23], 0, v[158:159]
	v_max_f32_e32 v54, 0, v54
	v_mul_f32_e32 v50, v50, v50
	v_mul_f32_e32 v55, v51, v51
	v_max_f32_e32 v51, 0, v56
	v_mul_f32_e32 v56, v52, v52
	v_max_f32_e32 v52, 0, v57
	v_max_f32_e32 v53, 0, v53
	v_pk_mul_f32 v[44:45], v[44:45], v[60:61] op_sel_hi:[1,0]
	v_pk_mul_f32 v[42:43], v[42:43], v[60:61] op_sel_hi:[1,0]
	v_lshl_add_u64 v[58:59], v[58:59], 0, v[98:99]
	v_mul_f32_e32 v54, v54, v54
	v_mul_f32_e32 v51, v51, v51
	v_mul_f32_e32 v52, v52, v52
	v_mul_f32_e32 v53, v53, v53
	v_cvt_pk_bf16_f32 v50, v54, v50
	v_pk_mul_f32 v[48:49], v[48:49], v[60:61] op_sel_hi:[1,0]
	v_pk_mul_f32 v[46:47], v[46:47], v[60:61] op_sel_hi:[1,0]
	v_max_f32_e32 v42, 0, v42
	v_max_f32_e32 v43, 0, v43
	v_max_f32_e32 v44, 0, v44
	v_cvt_pk_bf16_f32 v51, v51, v52
	v_cvt_pk_bf16_f32 v52, v61, v55
	v_cvt_pk_bf16_f32 v53, v56, v53
	global_store_dwordx4 v[58:59], v[50:53], off sc1
	v_max_f32_e32 v46, 0, v46
	v_max_f32_e32 v45, 0, v45
	v_mul_f32_e32 v50, v42, v42
	v_max_f32_e32 v42, 0, v47
	v_mul_f32_e32 v47, v43, v43
	v_max_f32_e32 v43, 0, v48
	v_mul_f32_e32 v48, v44, v44
	v_max_f32_e32 v44, 0, v49
	v_mul_f32_e32 v42, v42, v42
	v_mul_f32_e32 v43, v43, v43
	v_mul_f32_e32 v44, v44, v44
	v_mul_f32_e32 v46, v46, v46
	v_mul_f32_e32 v45, v45, v45
	v_cvt_pk_bf16_f32 v42, v46, v42
	v_cvt_pk_bf16_f32 v43, v43, v44
	v_cvt_pk_bf16_f32 v44, v50, v47
	v_pk_mul_f32 v[36:37], v[36:37], v[168:169] op_sel_hi:[1,0]
	v_max_f32_e32 v34, 0, v34
	v_cvt_pk_bf16_f32 v45, v48, v45
	global_store_dwordx4 v[58:59], v[42:45], off offset:64 sc1
	v_pk_mul_f32 v[40:41], v[40:41], v[168:169] op_sel_hi:[1,0]
	v_max_f32_e32 v35, 0, v35
	v_mul_f32_e32 v44, v34, v34
	v_max_f32_e32 v34, 0, v39
	v_max_f32_e32 v36, 0, v36
	v_lshl_add_u64 v[42:43], s[22:23], 0, v[160:161]
	v_max_f32_e32 v38, 0, v38
	v_mul_f32_e32 v34, v34, v34
	v_mul_f32_e32 v39, v35, v35
	v_max_f32_e32 v35, 0, v40
	v_mul_f32_e32 v40, v36, v36
	v_max_f32_e32 v36, 0, v41
	v_max_f32_e32 v37, 0, v37
	v_pk_mul_f32 v[28:29], v[28:29], v[168:169] op_sel_hi:[1,0]
	v_pk_mul_f32 v[26:27], v[26:27], v[168:169] op_sel_hi:[1,0]
	v_lshl_add_u64 v[42:43], v[42:43], 0, v[98:99]
	v_mul_f32_e32 v38, v38, v38
	v_mul_f32_e32 v35, v35, v35
	v_mul_f32_e32 v36, v36, v36
	v_mul_f32_e32 v37, v37, v37
	v_cvt_pk_bf16_f32 v34, v38, v34
	v_pk_mul_f32 v[32:33], v[32:33], v[168:169] op_sel_hi:[1,0]
	v_pk_mul_f32 v[30:31], v[30:31], v[168:169] op_sel_hi:[1,0]
	v_max_f32_e32 v26, 0, v26
	v_max_f32_e32 v27, 0, v27
	v_max_f32_e32 v28, 0, v28
	v_cvt_pk_bf16_f32 v35, v35, v36
	v_cvt_pk_bf16_f32 v36, v44, v39
	v_cvt_pk_bf16_f32 v37, v40, v37
	global_store_dwordx4 v[42:43], v[34:37], off sc1
	v_max_f32_e32 v30, 0, v30
	v_max_f32_e32 v29, 0, v29
	v_mul_f32_e32 v34, v26, v26
	v_max_f32_e32 v26, 0, v31
	v_mul_f32_e32 v31, v27, v27
	v_max_f32_e32 v27, 0, v32
	v_mul_f32_e32 v32, v28, v28
	v_max_f32_e32 v28, 0, v33
	v_mul_f32_e32 v26, v26, v26
	v_mul_f32_e32 v27, v27, v27
	v_mul_f32_e32 v28, v28, v28
	v_mul_f32_e32 v30, v30, v30
	v_mul_f32_e32 v29, v29, v29
	v_cvt_pk_bf16_f32 v26, v30, v26
	v_cvt_pk_bf16_f32 v27, v27, v28
	v_cvt_pk_bf16_f32 v28, v34, v31
	v_cvt_pk_bf16_f32 v29, v32, v29
	global_store_dwordx4 v[42:43], v[26:29], off offset:64 sc1
	s_and_b64 vcc, exec, s[38:39]
	s_mov_b64 s[0:1], -1
	v_mov_b32_e32 v28, v169
	v_pk_mul_f32 v[18:19], v[18:19], v[28:29] op_sel_hi:[1,0]
	v_pk_mul_f32 v[22:23], v[22:23], v[28:29] op_sel_hi:[1,0]
	v_pk_mul_f32 v[20:21], v[20:21], v[28:29] op_sel_hi:[1,0]
	v_max_f32_e32 v18, 0, v18
	v_pk_mul_f32 v[24:25], v[24:25], v[28:29] op_sel_hi:[1,0]
	v_mul_f32_e32 v29, v18, v18
	v_max_f32_e32 v18, 0, v23
	v_max_f32_e32 v19, 0, v19
	v_max_f32_e32 v20, 0, v20
	v_lshl_add_u64 v[26:27], s[22:23], 0, v[162:163]
	v_max_f32_e32 v22, 0, v22
	v_mul_f32_e32 v18, v18, v18
	v_mul_f32_e32 v23, v19, v19
	v_max_f32_e32 v19, 0, v24
	v_mul_f32_e32 v24, v20, v20
	v_max_f32_e32 v20, 0, v25
	v_max_f32_e32 v21, 0, v21
	v_pk_mul_f32 v[12:13], v[12:13], v[28:29] op_sel_hi:[1,0]
	v_pk_mul_f32 v[10:11], v[10:11], v[28:29] op_sel_hi:[1,0]
	v_lshl_add_u64 v[26:27], v[26:27], 0, v[98:99]
	v_mul_f32_e32 v22, v22, v22
	v_mul_f32_e32 v19, v19, v19
	v_mul_f32_e32 v20, v20, v20
	v_mul_f32_e32 v21, v21, v21
	v_cvt_pk_bf16_f32 v18, v22, v18
	v_pk_mul_f32 v[16:17], v[16:17], v[28:29] op_sel_hi:[1,0]
	v_pk_mul_f32 v[14:15], v[14:15], v[28:29] op_sel_hi:[1,0]
	v_max_f32_e32 v10, 0, v10
	v_max_f32_e32 v11, 0, v11
	v_max_f32_e32 v12, 0, v12
	v_cvt_pk_bf16_f32 v19, v19, v20
	v_cvt_pk_bf16_f32 v20, v29, v23
	v_cvt_pk_bf16_f32 v21, v24, v21
	global_store_dwordx4 v[26:27], v[18:21], off sc1
	v_max_f32_e32 v13, 0, v13
	v_max_f32_e32 v14, 0, v14
	v_mul_f32_e32 v18, v10, v10
	v_max_f32_e32 v10, 0, v15
	v_mul_f32_e32 v15, v11, v11
	v_max_f32_e32 v11, 0, v16
	v_mul_f32_e32 v16, v12, v12
	v_max_f32_e32 v12, 0, v17
	v_mul_f32_e32 v10, v10, v10
	v_mul_f32_e32 v11, v11, v11
	v_mul_f32_e32 v12, v12, v12
	v_mul_f32_e32 v13, v13, v13
	v_mul_f32_e32 v14, v14, v14
	v_cvt_pk_bf16_f32 v10, v14, v10
	v_cvt_pk_bf16_f32 v11, v11, v12
	v_cvt_pk_bf16_f32 v12, v18, v15
	v_cvt_pk_bf16_f32 v13, v16, v13
	global_store_dwordx4 v[26:27], v[10:13], off offset:64 sc1
	s_cbranch_vccnz .LBB0_38
	s_waitcnt vmcnt(16)
	v_add_f32_e32 v10, v6, v7
	v_add_f32_e32 v11, v8, v9
	v_add_f32_e32 v10, v10, v11
	v_add_f32_e32 v11, v2, v3
	v_add_f32_e32 v12, v4, v5
	v_add_f32_e32 v11, v11, v12
	v_add_f32_e32 v11, v11, v10
	ds_bpermute_b32 v12, v176, v11
	v_mov_b32_e32 v10, v0
	s_nop 0
	v_and_b32_e32 v13, 1, v10
	v_cmp_eq_u32_e32 vcc, 0, v13
	s_and_saveexec_b64 s[0:1], vcc
	s_cbranch_execz .LBB0_54
	s_waitcnt lgkmcnt(0)
	v_add_f32_e32 v11, v11, v12
	s_lshl_b32 s6, s45, 10
	v_fmamk_f32 v11, v11, 0x3a800000, v1
	s_and_b32 s6, s6, 0x400
	v_rsq_f32_e32 v11, v11
	s_add_i32 s6, s6, 0
	v_lshl_add_u32 v10, v10, 1, s6
	v_add_u32_e32 v10, 0x21000, v10
	ds_write_b32 v10, v11

; __device__ __forceinline__ int opaque_tid() { int t = threadIdx.x; asm volatile("" : "+v"(t)); return t; }
; __device__ __forceinline__ void rstd_load(const float* ss, RstdIni& ini, int pm) {
;     const int tid = opaque_tid();
;     const f32x4* q = (const f32x4*)(ss + (size_t)(pm * BM + (tid >> 1)) * 16 + (tid & 1) * 8);
;     ini.a = q[0]; ini.b = q[1];
; }
; template <class Epi>
; __device__ __forceinline__ void gemm_phase(PG8_LAS unsigned char* lds, const Gemm g, const StaticOrder& S, const Epi& E) {
;     ...
;         if (has_next) E.next_load(ini, nxt);
.LBB0_264:
	v_cndmask_b32_e64 v140, 0, 1, s[38:39]
	v_cmp_ne_u32_e64 s[36:37], 1, v140
	s_andn2_b64 vcc, exec, s[38:39]
	s_cbranch_vccnz .LBB0_266
	v_mov_b32_e32 v4, v0
	v_mov_b32_e32 v5, v99
	v_ashrrev_i32_e32 v2, 1, v4
	v_lshl_add_u32 v2, s16, 8, v2
	v_ashrrev_i32_e32 v3, 31, v2
	v_lshlrev_b64 v[2:3], 6, v[2:3]
	v_lshlrev_b32_e32 v4, 5, v4
	v_lshl_add_u64 v[2:3], s[98:99], 0, v[2:3]
	v_and_b32_e32 v4, 32, v4
	v_lshl_add_u64 v[6:7], v[2:3], 0, v[4:5]
	global_load_dwordx4 v[2:5], v[6:7], off offset:16
	s_nop 0
	global_load_dwordx4 v[6:9], v[6:7], off

; __device__ __forceinline__ int opaque_tid() { int t = threadIdx.x; asm volatile("" : "+v"(t)); return t; }
; #define PG8_LAS __attribute__((address_space(3)))
; __device__ __forceinline__ u32x4 pack8(f32x4 a, f32x4 b) { u32x4 w; w.x = cvt_pk_bf16(a[0], a[1]); w.y = cvt_pk_bf16(a[2], a[3]); w.z = cvt_pk_bf16(b[0], b[1]); w.w = cvt_pk_bf16(b[2], b[3]); return w; }
; __device__ __forceinline__ bf16x8 pack8(f32x4 a, f32x4 b) { u32x4 w = {cvtpk(a[0], a[1]), cvtpk(a[2], a[3]), cvtpk(b[0], b[1]), cvtpk(b[2], b[3])}; return *reinterpret_cast<bf16x8*>(&w); }
; __device__ __forceinline__ void rstd_store(PG8_LAS float* tab, const RstdIni& ini, int par) {
;     const int tid = opaque_tid();
;     float s = ((ini.a[0] + ini.a[1]) + (ini.a[2] + ini.a[3])) + ((ini.b[0] + ini.b[1]) + (ini.b[2] + ini.b[3]));
;     s += __shfl_xor(s, 1);
;     if (!(tid & 1)) tab[par * BM + (tid >> 1)] = __builtin_amdgcn_rsqf(s * (1.0f / 1024.0f) + 1e-6f);
; }
;     PG8_RSTD_HOOKS
;     __device__ __forceinline__ void operator()(const f32x4 (&acc)[2][2][4][2], const Unit& u, int wr, int wc, int fr, int fq, int par) const {
;     ...
;                 if (u.pn < 8) { const float rs2 = rs * rs;
;                     const f32x4 z0 = acc[ai][0][m][0] * acc[ai][1][m][0] * rs2, z1 = acc[ai][0][m][1] * acc[ai][1][m][1] * rs2;
;                     *(u32x4*)(Z + (size_t)row * 1024 + u.pn * 128 + wc * 32 + 8 * fq) = pack8(z0, z1);
;                 } else {
; #pragma unroll
;                     for (int bj = 0; bj < 2; ++bj)
;                         *(u32x4*)(GB + (size_t)row * 1024 + (u.pn - 8) * 256 + bj * HALF + wc * 32 + 8 * fq) = pack8(acc[ai][bj][m][0] * rs, acc[ai][bj][m][1] * rs);
;                 } }
.LBB0_298:
	v_lshl_add_u64 v[10:11], v[32:33], 0, s[86:87]
	v_lshl_add_u64 v[10:11], v[10:11], 0, v[98:99]
	s_and_b64 vcc, exec, s[36:37]
	s_mov_b64 s[0:1], -1
	global_store_dwordx4 v[10:11], v[26:29], off sc1
	s_cbranch_vccnz .LBB0_257
	s_waitcnt vmcnt(8)
	v_add_f32_e32 v10, v6, v7
	v_add_f32_e32 v11, v8, v9
	v_add_f32_e32 v10, v10, v11
	v_add_f32_e32 v11, v2, v3
	v_add_f32_e32 v12, v4, v5
	v_add_f32_e32 v11, v11, v12
	v_add_f32_e32 v11, v11, v10
	ds_bpermute_b32 v12, v168, v11
	v_mov_b32_e32 v10, v0
	s_nop 0
	v_and_b32_e32 v13, 1, v10
	v_cmp_eq_u32_e32 vcc, 0, v13
	s_and_saveexec_b64 s[0:1], vcc
	s_cbranch_execz .LBB0_301
	s_waitcnt lgkmcnt(0)
	v_add_f32_e32 v11, v11, v12
	s_lshl_b32 s6, s31, 10
	v_fmamk_f32 v11, v11, 0x3a800000, v1
	s_and_b32 s6, s6, 0x400
	v_rsq_f32_e32 v11, v11
	s_add_i32 s6, s6, 0
	v_lshl_add_u32 v10, v10, 1, s6
	v_add_u32_e32 v10, 0x21000, v10
	ds_write_b32 v10, v11
